# v13 + skip over-issued LDS-DMA tiles in the peeled last attention step
# speedup vs baseline: 1.0043x; 1.0020x over previous
; __device__ __forceinline__ void attn_mla_unit(LAS unsigned char* lds, const bf16_t* __restrict__ QM, const bf16_t* __restrict__ Kb, const bf16_t* __restrict__ KR, const bf16_t* __restrict__ VT, bf16_t* O,
;                                               int qrow0, int b, int h, int ntiles) {
;     ...
;     int t = 1;
;     for (; t + 1 < ntiles; t += 2) { M_STEP(pB0, pB1, pA0, pA1); M_STEP(pA0, pA1, pB0, pB1); }
;     M_STEP(pB0, pB1, pA0, pA1);
.LBB0_818:
	s_mul_i32 s2, s15, 0x3400
	s_add_i32 s2, s2, 0
	v_add_u32_e32 v72, s2, v193
	ds_read_b128 v[64:67], v72
	ds_read_b128 v[68:71], v72 offset:6656
	ds_read_b128 v[156:159], v72 offset:32
	ds_read_b128 v[152:155], v72 offset:6688
	ds_read_b128 v[148:151], v72 offset:64
	ds_read_b128 v[144:147], v72 offset:6720
	ds_read_b128 v[140:143], v72 offset:96
	ds_read_b128 v[136:139], v72 offset:6752
	ds_read_b128 v[132:135], v72 offset:128
	ds_read_b128 v[128:131], v72 offset:6784
	ds_read_b128 v[124:127], v72 offset:160
	ds_read_b128 v[120:123], v72 offset:6816
	s_and_b64 vcc, exec, s[42:43]
	s_branch .LBB0_827
	s_mul_i32 s2, s13, 0x2400
	s_add_i32 s2, s2, 0
	s_add_i32 s2, s2, 0x9c00
	s_lshl_b32 s14, s12, 6
	s_mov_b64 s[42:43], -1
	s_and_b64 vcc, exec, s[34:35]
	s_cbranch_vccnz .LBB0_851
	s_mul_i32 s15, s11, 0x3400
	s_andn2_b64 vcc, exec, s[42:43]
	s_add_i32 s15, s15, 0
	s_cbranch_vccz .LBB0_852

; #define LAS __attribute__((address_space(3)))
; #define MFMA32(a, b, c) __builtin_amdgcn_mfma_f32_32x32x16_bf16((a), (b), (c), 0, 0, 0)
; #define SGB(mask, n) __builtin_amdgcn_sched_group_barrier((mask), (n), 0)
; #define SBAR0() __builtin_amdgcn_sched_barrier(0)
; template <int NKD, int KSTRIDE, int VSTRIDE> __device__ __forceinline__ void att_regionA(const bf16x8 (&kf)[2 * NKD], const bf16x8 (&qr)[NKD], f32x16& c0, f32x16& c1, ...
;     SBAR0();
;     __builtin_amdgcn_s_setprio(1);
;     f32x16 z;
; #pragma unroll
;     for (int r = 0; r < 16; ++r) z[r] = 0.f;
; #pragma unroll
;     for (int d0 = 0; d0 < NKD; ++d0) { c0 = MFMA32(kf[2 * d0], qr[d0], d0 == 0 ? z : c0); c1 = MFMA32(kf[2 * d0 + 1], qr[d0], d0 == 0 ? z : c1); }
;     float s0 = 0.f, s1 = 0.f;
; #pragma unroll
;     for (int r = 0; r < 16; ++r) { s0 += pp0[r]; s1 += pp1[r]; }
;     pf[0] = pack8<0>(pp0); pf[1] = pack8<8>(pp0); pf[2] = pack8<0>(pp1); pf[3] = pack8<8>(pp1);
;     lrun += s0 + s1;
;     att_vpre<VSTRIDE>(vb, vf);
;     asm volatile("" : "+v"(lrun), "+v"(pf[0]), "+v"(pf[1]), "+v"(pf[2]), "+v"(pf[3]));
;     SGB(0x008, NKD / 2);
; #pragma unroll
;     for (int i = 0; i < 2 * NKD - NKD / 2; ++i) { SGB(0x008, 1); SGB(0x002, 48 / (2 * NKD - NKD / 2)); }
;     SGB(0x100, 8);
;     __builtin_amdgcn_s_setprio(0);
;     SBAR0();
; }
.LBB0_827:
	s_mul_i32 s2, s10, 0x2400
	s_add_i32 s2, s2, 0
	v_add_u32_e32 v193, s2, v163
	s_setprio 1
	s_waitcnt lgkmcnt(11)
	v_mfma_f32_32x32x16_bf16 v[80:95], v[64:67], v[116:119], v[228:243]
	s_waitcnt lgkmcnt(10)
	v_mfma_f32_32x32x16_bf16 v[64:79], v[68:71], v[116:119], v[228:243]
	s_waitcnt lgkmcnt(9)
	v_mfma_f32_32x32x16_bf16 v[80:95], v[156:159], v[112:115], v[80:95]
	s_waitcnt lgkmcnt(8)
	v_mfma_f32_32x32x16_bf16 v[64:79], v[152:155], v[112:115], v[64:79]
	v_add_f32_e32 v112, 0, v48
	v_add_f32_e32 v113, 0, v32
	v_add_f32_e32 v112, v49, v112
	v_add_f32_e32 v113, v33, v113
	v_add_f32_e32 v112, v50, v112
	s_waitcnt lgkmcnt(7)
	v_mfma_f32_32x32x16_bf16 v[80:95], v[148:151], v[108:111], v[80:95]
	v_add_f32_e32 v113, v34, v113
	v_add_f32_e32 v112, v51, v112
	v_add_f32_e32 v113, v35, v113
	v_add_f32_e32 v112, v52, v112
	v_add_f32_e32 v113, v36, v113
	s_waitcnt lgkmcnt(6)
	v_mfma_f32_32x32x16_bf16 v[64:79], v[144:147], v[108:111], v[64:79]
	v_add_f32_e32 v108, v53, v112
	v_add_f32_e32 v109, v37, v113
	v_add_f32_e32 v108, v54, v108
	v_add_f32_e32 v109, v38, v109
	v_add_f32_e32 v108, v55, v108
	s_waitcnt lgkmcnt(5)
	v_mfma_f32_32x32x16_bf16 v[80:95], v[140:143], v[104:107], v[80:95]
	v_add_f32_e32 v109, v39, v109
	v_add_f32_e32 v108, v56, v108
	v_add_f32_e32 v109, v40, v109
	v_add_f32_e32 v108, v57, v108
	v_add_f32_e32 v109, v41, v109
	s_waitcnt lgkmcnt(4)
	v_mfma_f32_32x32x16_bf16 v[64:79], v[136:139], v[104:107], v[64:79]
	v_add_f32_e32 v104, v58, v108
	v_add_f32_e32 v105, v42, v109
	v_add_f32_e32 v104, v59, v104
	v_add_f32_e32 v105, v43, v105
	v_add_f32_e32 v104, v60, v104
	s_waitcnt lgkmcnt(3)
	v_mfma_f32_32x32x16_bf16 v[80:95], v[132:135], v[100:103], v[80:95]
	v_add_f32_e32 v105, v44, v105
	v_add_f32_e32 v104, v61, v104
	v_add_f32_e32 v105, v45, v105
	v_add_f32_e32 v104, v62, v104
	v_add_f32_e32 v105, v46, v105
	s_waitcnt lgkmcnt(2)
	v_mfma_f32_32x32x16_bf16 v[64:79], v[128:131], v[100:103], v[64:79]
	v_add_f32_e32 v116, v63, v104
	v_add_f32_e32 v117, v47, v105
	v_cvt_pk_bf16_f32 v48, v48, v49
	v_cvt_pk_bf16_f32 v49, v50, v51
	v_cvt_pk_bf16_f32 v50, v52, v53
	s_waitcnt lgkmcnt(1)
	v_mfma_f32_32x32x16_bf16 v[80:95], v[124:127], v[96:99], v[80:95]
	v_cvt_pk_bf16_f32 v51, v54, v55
	v_cvt_pk_bf16_f32 v52, v56, v57
	v_cvt_pk_bf16_f32 v53, v58, v59
	v_cvt_pk_bf16_f32 v54, v60, v61
	v_cvt_pk_bf16_f32 v55, v62, v63
	s_waitcnt lgkmcnt(0)
	v_mfma_f32_32x32x16_bf16 v[64:79], v[120:123], v[96:99], v[64:79]
	v_cvt_pk_bf16_f32 v32, v32, v33
	v_cvt_pk_bf16_f32 v33, v34, v35
	v_cvt_pk_bf16_f32 v34, v36, v37
	v_cvt_pk_bf16_f32 v35, v38, v39
	v_cvt_pk_bf16_f32 v36, v40, v41
	v_cvt_pk_bf16_f32 v37, v42, v43
	ds_read_b128 v[40:43], v193 offset:39936
	ds_read_b128 v[56:59], v193 offset:39968
	ds_read_b128 v[60:63], v193 offset:40000
	ds_read_b128 v[96:99], v193 offset:40032
	ds_read_b128 v[100:103], v193 offset:44544
	ds_read_b128 v[104:107], v193 offset:44576
	ds_read_b128 v[108:111], v193 offset:44608
	ds_read_b128 v[112:115], v193 offset:44640
	v_cvt_pk_bf16_f32 v38, v44, v45
	v_add_f32_e32 v44, v117, v116
	v_cvt_pk_bf16_f32 v39, v46, v47
	v_add_f32_e32 v116, v194, v44
	s_setprio 0
	s_and_b64 vcc, exec, s[44:45]
	s_branch .LBB0_835
	s_mul_i32 s2, s13, 0x2400
	s_add_i32 s2, s2, 0
	s_add_i32 s2, s2, 0x9c00
	s_lshl_b32 s13, s12, 6
	s_mov_b64 s[42:43], -1
	s_and_b64 vcc, exec, s[34:35]
	s_cbranch_vccnz .LBB0_856
	s_mulk_i32 s11, 0x3400
	s_andn2_b64 vcc, exec, s[42:43]
	s_add_i32 s11, s11, 0
	s_cbranch_vccz .LBB0_857

; template <int NKD, int KSTRIDE, int VSTRIDE> __device__ __forceinline__ void att_regionA(const bf16x8 (&kf)[2 * NKD], const bf16x8 (&qr)[NKD], f32x16& c0, f32x16& c1, ...
;     SBAR0();
;     __builtin_amdgcn_s_setprio(1);
;     f32x16 z;
; #pragma unroll
;     for (int r = 0; r < 16; ++r) z[r] = 0.f;
; #pragma unroll
;     for (int d0 = 0; d0 < NKD; ++d0) { c0 = MFMA32(kf[2 * d0], qr[d0], d0 == 0 ? z : c0); c1 = MFMA32(kf[2 * d0 + 1], qr[d0], d0 == 0 ? z : c1); }
;     float s0 = 0.f, s1 = 0.f;
; #pragma unroll
;     for (int r = 0; r < 16; ++r) { s0 += pp0[r]; s1 += pp1[r]; }
;     pf[0] = pack8<0>(pp0); pf[1] = pack8<8>(pp0); pf[2] = pack8<0>(pp1); pf[3] = pack8<8>(pp1);
;     lrun += s0 + s1;
;     att_vpre<VSTRIDE>(vb, vf);
;     asm volatile("" : "+v"(lrun), "+v"(pf[0]), "+v"(pf[1]), "+v"(pf[2]), "+v"(pf[3]));
;     SGB(0x008, NKD / 2);
; #pragma unroll
;     for (int i = 0; i < 2 * NKD - NKD / 2; ++i) { SGB(0x008, 1); SGB(0x002, 48 / (2 * NKD - NKD / 2)); }
;     SGB(0x100, 8);
;     __builtin_amdgcn_s_setprio(0);
;     SBAR0();
; }
; __device__ __forceinline__ bool att_decide(f32x16& c0, f32x16& c1, float& mhat, float& lrun, float& fsc) {
;     c0 = c0 - mhat; c1 = c1 - mhat;
;     float ra = fmaxf(fmaxf(c0[0], c0[1]), c0[2]), rb = fmaxf(fmaxf(c1[0], c1[1]), c1[2]);
; #pragma unroll
;     for (int r = 3; r < 15; r += 2) { ra = fmaxf(fmaxf(ra, c0[r]), c0[r + 1]); rb = fmaxf(fmaxf(rb, c1[r]), c1[r + 1]); }
;     float rm = fmaxf(fmaxf(ra, rb), fmaxf(c0[15], c1[15]));
;     { auto rr = __builtin_amdgcn_permlane32_swap(__float_as_uint(rm), __float_as_uint(rm), false, false); rm = fmaxf(__uint_as_float(rr[0]), __uint_as_float(rr[1])); }
;     bool resc = false; fsc = 1.f;
;     if (__builtin_expect(__any(rm > ATT_THR), 0)) { asm volatile("; rare: reference update" ::: "memory"); const float dl = fmaxf(rm, 0.f); mhat += dl; fsc = __builtin_amdgcn_exp2f(-dl); lrun *= fsc; c0 = c0 - dl; c1 = c1 - dl; resc = true; }
; __device__ __forceinline__ void attn_diff_unit(LAS unsigned char* lds, const bf16_t* __restrict__ Q, const bf16_t* __restrict__ Kb, const bf16_t* __restrict__ VT, bf16_t* O,
;                                                int qrow0, int b, int h, int ntiles, float lam, const float* subln_g) {
;     ...
;     int t = 1;
;     for (; t + 1 < ntiles; t += 2) { D_STEP(pB0, pB1, pA0, pA1); D_STEP(pA0, pA1, pB0, pB1); }
;     D_STEP(pB0, pB1, pA0, pA1);
.LBB0_1123:
	s_mul_i32 s15, s28, 0x4400
	s_add_i32 s15, s15, 0
	v_add_u32_e32 v104, s15, v248
	ds_read_b128 v[96:99], v104
	ds_read_b128 v[100:103], v104 offset:8704
	ds_read_b128 v[166:169], v104 offset:32
	ds_read_b128 v[162:165], v104 offset:8736
	ds_read_b128 v[158:161], v104 offset:64
	ds_read_b128 v[154:157], v104 offset:8768
	ds_read_b128 v[150:153], v104 offset:96
	ds_read_b128 v[146:149], v104 offset:8800
	s_and_b64 vcc, exec, s[38:39]
	s_mul_i32 s15, s80, 0x4400
	s_branch .LBB0_1125
	s_ashr_i32 s47, s46, 31
	s_lshl_b64 s[28:29], s[46:47], 17
	s_add_u32 s28, s44, s28
	s_addc_u32 s29, s45, s29
	s_add_i32 s17, s15, 0
	v_lshl_add_u64 v[104:105], v[212:213], 1, s[28:29]
	s_add_i32 s33, s17, s14
	s_mov_b32 s47, m0
	s_mov_b32 m0, s33
	s_nop 0
	global_load_lds_dwordx4 v[104:105], off
	s_mov_b32 m0, s47
	v_lshl_add_u64 v[104:105], v[214:215], 1, s[28:29]
	s_add_i32 s17, s17, s16
	s_mov_b32 s28, m0
	s_mov_b32 m0, s17
	s_nop 0
	global_load_lds_dwordx4 v[104:105], off
	s_mov_b32 m0, s28
.LBB0_1125:
	s_mul_i32 s17, s13, 0x4800
	s_add_i32 s17, s17, 0
	v_add_u32_e32 v179, s17, v232
	s_setprio 1
	s_waitcnt lgkmcnt(7)
	v_mfma_f32_32x32x16_bf16 v[114:129], v[96:99], v[142:145], 0
	s_waitcnt lgkmcnt(6)
	v_mfma_f32_32x32x16_bf16 v[98:113], v[100:103], v[142:145], 0
	s_waitcnt lgkmcnt(5)
	v_mfma_f32_32x32x16_bf16 v[114:129], v[166:169], v[138:141], v[114:129]
	v_add_f32_e32 v96, 0, v80
	v_add_f32_e32 v97, 0, v64
	v_add_f32_e32 v96, v81, v96
	v_add_f32_e32 v97, v65, v97
	v_add_f32_e32 v96, v82, v96
	v_add_f32_e32 v97, v66, v97
	v_add_f32_e32 v96, v83, v96
	v_add_f32_e32 v97, v67, v97
	s_waitcnt lgkmcnt(4)
	v_mfma_f32_32x32x16_bf16 v[98:113], v[162:165], v[138:141], v[98:113]
	v_add_f32_e32 v96, v84, v96
	v_add_f32_e32 v97, v68, v97
	v_add_f32_e32 v96, v85, v96
	v_add_f32_e32 v97, v69, v97
	v_add_f32_e32 v96, v86, v96
	v_add_f32_e32 v97, v70, v97
	v_add_f32_e32 v96, v87, v96
	v_add_f32_e32 v97, v71, v97
	s_waitcnt lgkmcnt(3)
	v_mfma_f32_32x32x16_bf16 v[114:129], v[158:161], v[134:137], v[114:129]
	v_add_f32_e32 v96, v88, v96
	v_add_f32_e32 v97, v72, v97
	v_add_f32_e32 v96, v89, v96
	v_add_f32_e32 v97, v73, v97
	v_add_f32_e32 v96, v90, v96
	v_add_f32_e32 v97, v74, v97
	v_add_f32_e32 v96, v91, v96
	v_add_f32_e32 v97, v75, v97
	s_waitcnt lgkmcnt(2)
	v_mfma_f32_32x32x16_bf16 v[98:113], v[154:157], v[134:137], v[98:113]
	v_add_f32_e32 v96, v92, v96
	v_add_f32_e32 v97, v76, v97
	v_add_f32_e32 v96, v93, v96
	v_add_f32_e32 v97, v77, v97
	v_add_f32_e32 v96, v94, v96
	v_add_f32_e32 v97, v78, v97
	v_add_f32_e32 v96, v95, v96
	v_add_f32_e32 v97, v79, v97
	s_waitcnt lgkmcnt(1)
	v_mfma_f32_32x32x16_bf16 v[114:129], v[150:153], v[130:133], v[114:129]
	v_cvt_pk_bf16_f32 v134, v80, v81
	v_cvt_pk_bf16_f32 v135, v82, v83
	v_cvt_pk_bf16_f32 v136, v84, v85
	v_cvt_pk_bf16_f32 v137, v86, v87
	v_cvt_pk_bf16_f32 v138, v88, v89
	v_cvt_pk_bf16_f32 v139, v90, v91
	v_cvt_pk_bf16_f32 v140, v92, v93
	v_cvt_pk_bf16_f32 v141, v94, v95
	s_waitcnt lgkmcnt(0)
	v_mfma_f32_32x32x16_bf16 v[98:113], v[146:149], v[130:133], v[98:113]
	v_cvt_pk_bf16_f32 v130, v64, v65
	v_cvt_pk_bf16_f32 v131, v66, v67
	v_cvt_pk_bf16_f32 v132, v68, v69
	v_cvt_pk_bf16_f32 v133, v70, v71
	v_cvt_pk_bf16_f32 v142, v72, v73
	v_cvt_pk_bf16_f32 v143, v74, v75
	v_cvt_pk_bf16_f32 v144, v76, v77
	v_cvt_pk_bf16_f32 v145, v78, v79
	ds_read_b128 v[174:177], v179 offset:52224
	ds_read_b128 v[170:173], v179 offset:52256
	ds_read_b128 v[166:169], v179 offset:52288
	ds_read_b128 v[162:165], v179 offset:52320
	ds_read_b128 v[158:161], v179 offset:56832
	ds_read_b128 v[154:157], v179 offset:56864
	ds_read_b128 v[150:153], v179 offset:56896
	ds_read_b128 v[146:149], v179 offset:56928
	v_add_f32_e32 v64, v97, v96
	v_add_f32_e32 v178, v201, v64
	s_setprio 0
	s_and_b64 vcc, exec, s[40:41]
	s_branch .LBB0_1127
	s_ashr_i32 s47, s46, 31
	s_lshl_b64 s[28:29], s[46:47], 17
	s_add_u32 s28, s44, s28
	s_addc_u32 s29, s45, s29
	s_add_i32 s17, s15, 0
	v_lshl_add_u64 v[64:65], v[212:213], 1, s[28:29]
	s_add_i32 s14, s17, s14
	s_mov_b32 s33, m0
	s_mov_b32 m0, s14
	s_nop 0
	global_load_lds_dwordx4 v[64:65], off
	s_mov_b32 m0, s33
	v_lshl_add_u64 v[64:65], v[214:215], 1, s[28:29]
	s_add_i32 s14, s17, s16
	s_mov_b32 s16, m0
	s_mov_b32 m0, s14
	s_nop 0
	global_load_lds_dwordx4 v[64:65], off
	s_mov_b32 m0, s16
.LBB0_1127:
	v_sub_f32_e32 v66, v116, v250
	v_sub_f32_e32 v65, v115, v250
	v_sub_f32_e32 v64, v114, v250
	v_sub_f32_e32 v84, v100, v250
	v_sub_f32_e32 v83, v99, v250
	v_sub_f32_e32 v82, v98, v250
	v_sub_f32_e32 v68, v118, v250
	v_sub_f32_e32 v67, v117, v250
	v_sub_f32_e32 v86, v102, v250
	v_sub_f32_e32 v85, v101, v250
	v_max3_f32 v80, v64, v65, v66
	v_max3_f32 v81, v82, v83, v84
	v_sub_f32_e32 v70, v120, v250
	v_sub_f32_e32 v69, v119, v250
	v_sub_f32_e32 v88, v104, v250
	v_sub_f32_e32 v87, v103, v250
	v_max3_f32 v80, v80, v67, v68
	v_max3_f32 v81, v81, v85, v86
	v_sub_f32_e32 v72, v122, v250
	v_sub_f32_e32 v71, v121, v250
	v_sub_f32_e32 v90, v106, v250
	v_sub_f32_e32 v89, v105, v250
	v_max3_f32 v80, v80, v69, v70
	v_max3_f32 v81, v81, v87, v88
	v_sub_f32_e32 v74, v124, v250
	v_sub_f32_e32 v73, v123, v250
	v_sub_f32_e32 v92, v108, v250
	v_sub_f32_e32 v91, v107, v250
	v_max3_f32 v80, v80, v71, v72
	v_max3_f32 v81, v81, v89, v90
	v_sub_f32_e32 v76, v126, v250
	v_sub_f32_e32 v75, v125, v250
	v_sub_f32_e32 v94, v110, v250
	v_sub_f32_e32 v93, v109, v250
	v_max3_f32 v80, v80, v73, v74
	v_max3_f32 v81, v81, v91, v92
	v_sub_f32_e32 v79, v129, v250
	v_sub_f32_e32 v78, v128, v250
	v_sub_f32_e32 v77, v127, v250
	v_sub_f32_e32 v97, v113, v250
	v_sub_f32_e32 v96, v112, v250
	v_sub_f32_e32 v95, v111, v250
	v_max3_f32 v80, v80, v75, v76
	v_max3_f32 v81, v81, v93, v94
	v_max3_f32 v80, v80, v77, v78
	v_max3_f32 v81, v81, v95, v96
	v_max_f32_e32 v98, v79, v97
	v_max3_f32 v80, v80, v81, v98
	v_mov_b32_e32 v81, v80
	s_nop 1
	v_permlane32_swap_b32_e32 v80, v81
	v_max_f32_e32 v81, v81, v81
	v_max_f32_e32 v80, v80, v80
	v_max_f32_e32 v80, v80, v81
	v_cmp_lt_f32_e32 vcc, s67, v80
	s_cmp_lg_u64 vcc, 0
	s_cselect_b64 s[48:49], -1, 0
	s_cbranch_vccnz .LBB0_1137
	v_mov_b32_e32 v98, 1.0
	s_and_b64 vcc, exec, s[38:39]
	s_branch .LBB0_1130

; #define LAS __attribute__((address_space(3)))
; #define MFMA32(a, b, c) __builtin_amdgcn_mfma_f32_32x32x16_bf16((a), (b), (c), 0, 0, 0)
; #define SGB(mask, n) __builtin_amdgcn_sched_group_barrier((mask), (n), 0)
; #define SBAR0() __builtin_amdgcn_sched_barrier(0)
; template <int NBLK, int VSTRIDE> __device__ __forceinline__ void att_regionB(const LAS unsigned char* vb, const bf16x8 (&pf)[4], f32x16 (&o)[NBLK], f32x16& c0, f32x16& c1, const bf16x8 (&vf)[8], bool doexp) {
;     SBAR0();
;     __builtin_amdgcn_s_setprio(1);
;     bf16x8 vg[8];
;     if (NBLK == 4) {
; #pragma unroll
;         for (int i = 0; i < 8; ++i) vg[i] = *(const LAS bf16x8*)(vb + (2 + (i >> 2)) * 32 * VSTRIDE + (i & 3) * 32);
;     }
; #pragma unroll
;     for (int i = 0; i < 8; ++i) o[i >> 2] = MFMA32(pf[i & 3], vf[i], o[i >> 2]);
;     if (NBLK == 4) {
; #pragma unroll
;         for (int i = 0; i < 8; ++i) o[(NBLK == 4 ? 2 : 0) + (i >> 2)] = MFMA32(pf[i & 3], vg[i], o[(NBLK == 4 ? 2 : 0) + (i >> 2)]);
;     }
;     if (doexp) {
; #pragma unroll
;         for (int r = 0; r < 16; ++r) { c0[r] = __builtin_amdgcn_exp2f(c0[r]); c1[r] = __builtin_amdgcn_exp2f(c1[r]); }
;         asm volatile("" : "+v"(c0), "+v"(c1));
;         if (NBLK == 4) {
; #pragma unroll
;             for (int i = 0; i < 8; ++i) { SGB(0x008, 1); SGB(0x400, 2); SGB(0x100, 1); }
; #pragma unroll
;             for (int i = 0; i < 8; ++i) { SGB(0x008, 1); SGB(0x400, 2); }
;         } else {
; #pragma unroll
;             for (int i = 0; i < 8; ++i) { SGB(0x008, 1); SGB(0x400, 4); }
;         }
;     }
;     __builtin_amdgcn_s_setprio(0);
;     SBAR0();
; }
.LBB0_1130:
	v_add_u32_e32 v99, 0xcc00, v179
	s_setprio 1
	s_waitcnt lgkmcnt(7)
	v_mfma_f32_32x32x16_bf16 v[0:15], v[134:137], v[174:177], v[0:15]
	v_exp_f32_e32 v80, v64
	v_exp_f32_e32 v64, v82
	ds_read_b128 v[100:103], v179 offset:61440
	s_waitcnt lgkmcnt(7)
	v_mfma_f32_32x32x16_bf16 v[0:15], v[138:141], v[170:173], v[0:15]
	v_exp_f32_e32 v81, v65
	v_exp_f32_e32 v65, v83
	ds_read_b128 v[104:107], v179 offset:61472
	s_waitcnt lgkmcnt(7)
	v_mfma_f32_32x32x16_bf16 v[0:15], v[130:133], v[166:169], v[0:15]
	v_exp_f32_e32 v82, v66
	v_exp_f32_e32 v66, v84
	ds_read_b128 v[108:111], v179 offset:61504
	s_waitcnt lgkmcnt(7)
	v_mfma_f32_32x32x16_bf16 v[0:15], v[142:145], v[162:165], v[0:15]
	v_exp_f32_e32 v83, v67
	v_exp_f32_e32 v67, v85
	ds_read_b128 v[112:115], v179 offset:61536
	s_waitcnt lgkmcnt(7)
	v_mfma_f32_32x32x16_bf16 v[48:63], v[134:137], v[158:161], v[48:63]
	v_exp_f32_e32 v84, v68
	v_exp_f32_e32 v68, v86
	ds_read_b128 v[116:119], v99 offset:13824
	s_waitcnt lgkmcnt(7)
	v_mfma_f32_32x32x16_bf16 v[48:63], v[138:141], v[154:157], v[48:63]
	v_exp_f32_e32 v85, v69
	v_exp_f32_e32 v69, v87
	ds_read_b128 v[120:123], v99 offset:13856
	s_waitcnt lgkmcnt(7)
	v_mfma_f32_32x32x16_bf16 v[48:63], v[130:133], v[150:153], v[48:63]
	v_exp_f32_e32 v86, v70
	v_exp_f32_e32 v70, v88
	ds_read_b128 v[124:127], v99 offset:13888
	s_waitcnt lgkmcnt(7)
	v_mfma_f32_32x32x16_bf16 v[48:63], v[142:145], v[146:149], v[48:63]
	v_exp_f32_e32 v87, v71
	v_exp_f32_e32 v71, v89
	ds_read_b128 v[146:149], v99 offset:13920
	s_waitcnt lgkmcnt(7)
	v_mfma_f32_32x32x16_bf16 v[16:31], v[134:137], v[100:103], v[16:31]
	v_exp_f32_e32 v88, v72
	v_exp_f32_e32 v72, v90
	s_waitcnt lgkmcnt(6)
	v_mfma_f32_32x32x16_bf16 v[16:31], v[138:141], v[104:107], v[16:31]
	v_exp_f32_e32 v89, v73
	v_exp_f32_e32 v73, v91
	s_waitcnt lgkmcnt(5)
	v_mfma_f32_32x32x16_bf16 v[16:31], v[130:133], v[108:111], v[16:31]
	v_exp_f32_e32 v90, v74
	v_exp_f32_e32 v74, v92
	s_waitcnt lgkmcnt(4)
	v_mfma_f32_32x32x16_bf16 v[16:31], v[142:145], v[112:115], v[16:31]
	v_exp_f32_e32 v91, v75
	v_exp_f32_e32 v75, v93
	s_waitcnt lgkmcnt(3)
	v_mfma_f32_32x32x16_bf16 v[32:47], v[134:137], v[116:119], v[32:47]
	v_exp_f32_e32 v92, v76
	v_exp_f32_e32 v76, v94
	s_waitcnt lgkmcnt(2)
	v_mfma_f32_32x32x16_bf16 v[32:47], v[138:141], v[120:123], v[32:47]
	v_exp_f32_e32 v93, v77
	v_exp_f32_e32 v77, v95
	s_waitcnt lgkmcnt(1)
	v_mfma_f32_32x32x16_bf16 v[32:47], v[130:133], v[124:127], v[32:47]
	v_exp_f32_e32 v94, v78
	v_exp_f32_e32 v78, v96
	s_waitcnt lgkmcnt(0)
	v_mfma_f32_32x32x16_bf16 v[32:47], v[142:145], v[146:149], v[32:47]
	v_exp_f32_e32 v95, v79
	v_exp_f32_e32 v79, v97
	s_setprio 0
	s_and_b64 vcc, exec, s[40:41]
	s_branch .LBB0_1132
	s_ashr_i32 s47, s46, 31
	s_lshl_b64 s[14:15], s[46:47], 7
	s_add_u32 s14, s34, s14
	s_mulk_i32 s2, 0x4800
	s_addc_u32 s15, s35, s15
	s_add_i32 s2, s2, 0
	s_add_i32 s2, s2, 0xcc00
	v_lshl_add_u64 v[96:97], v[206:207], 1, s[14:15]
	s_add_i32 s3, s2, s3
	s_mov_b32 s16, m0
	s_mov_b32 m0, s3
	s_nop 0
	global_load_lds_dwordx4 v[96:97], off
	s_mov_b32 m0, s16
	v_lshl_add_u64 v[96:97], v[208:209], 1, s[14:15]
	s_add_i32 s3, s2, s11
	s_mov_b32 s11, m0
	s_mov_b32 m0, s3
	s_nop 0
	global_load_lds_dwordx4 v[96:97], off
	s_mov_b32 m0, s11
	v_lshl_add_u64 v[96:97], v[210:211], 1, s[14:15]
	s_add_i32 s2, s2, s12
	s_mov_b32 s3, m0
	s_mov_b32 m0, s2
	s_nop 0
	global_load_lds_dwordx4 v[96:97], off
	s_mov_b32 m0, s3

; __device__ __forceinline__ bool att_decide(f32x16& c0, f32x16& c1, float& mhat, float& lrun, float& fsc) {
;     ...
;     if (__builtin_expect(__any(rm > ATT_THR), 0)) { asm volatile("; rare: reference update" ::: "memory"); const float dl = fmaxf(rm, 0.f); mhat += dl; fsc = __builtin_amdgcn_exp2f(-dl); lrun *= fsc; c0 = c0 - dl; c1 = c1 - dl; resc = true; }
.LBB0_1137:
	v_max_f32_e32 v80, v80, v80
	v_max_f32_e32 v80, 0, v80
	v_exp_f32_e64 v98, -v80
	v_sub_f32_e32 v79, v79, v80
	v_sub_f32_e32 v78, v78, v80
	v_sub_f32_e32 v77, v77, v80
	v_sub_f32_e32 v76, v76, v80
	v_sub_f32_e32 v75, v75, v80
	v_sub_f32_e32 v74, v74, v80
	v_sub_f32_e32 v73, v73, v80
	v_sub_f32_e32 v72, v72, v80
	v_sub_f32_e32 v71, v71, v80
	v_sub_f32_e32 v70, v70, v80
	v_sub_f32_e32 v69, v69, v80
	v_sub_f32_e32 v68, v68, v80
	v_sub_f32_e32 v67, v67, v80
	v_sub_f32_e32 v66, v66, v80
	v_sub_f32_e32 v65, v65, v80
	v_sub_f32_e32 v64, v64, v80
	v_sub_f32_e32 v97, v97, v80
	v_sub_f32_e32 v96, v96, v80
	v_sub_f32_e32 v95, v95, v80
	v_sub_f32_e32 v94, v94, v80
	v_sub_f32_e32 v93, v93, v80
	v_sub_f32_e32 v92, v92, v80
	v_sub_f32_e32 v91, v91, v80
	v_sub_f32_e32 v90, v90, v80
	v_sub_f32_e32 v89, v89, v80
	v_sub_f32_e32 v88, v88, v80
	v_sub_f32_e32 v87, v87, v80
	v_sub_f32_e32 v86, v86, v80
	v_sub_f32_e32 v85, v85, v80
	v_sub_f32_e32 v84, v84, v80
	v_sub_f32_e32 v83, v83, v80
	v_sub_f32_e32 v82, v82, v80
	v_mul_f32_e32 v178, v178, v98
	s_and_b64 vcc, exec, s[38:39]
	s_nop 0
	s_branch .LBB0_1130
